# prep: weight-transpose tile loads issued together with one wait (on top of pipelined merge)
# speedup vs baseline: 1.1275x; 1.0234x over previous
.LBB0_25:
	s_cmp_gt_i32 s6, -1
	s_cselect_b64 s[28:29], -1, 0
	s_lshl_b32 s27, s34, 6
	s_lshl_b64 s[34:35], s[6:7], 2
	s_add_u32 s0, s0, s34
	s_addc_u32 s1, s1, s35
	v_mov_b32_e32 v145, v35
	v_lshl_add_u64 v[2:3], s[0:1], 0, v[144:145]
	v_or_b32_e32 v4, s27, v175
	v_mad_u64_u32 v[8:9], s[34:35], s26, v4, 0
	s_lshl_b32 s0, s26, 5
	s_mov_b32 s1, 0
	v_lshl_add_u64 v[8:9], v[8:9], 2, v[2:3]
	s_andn2_b64 vcc, exec, s[28:29]
	s_cbranch_vccnz .Lpz_zero
	global_load_dword v10, v[8:9], off
	v_lshl_add_u64 v[8:9], v[8:9], 0, s[0:1]
	global_load_dword v11, v[8:9], off
	v_lshl_add_u64 v[8:9], v[8:9], 0, s[0:1]
	global_load_dword v12, v[8:9], off
	v_lshl_add_u64 v[8:9], v[8:9], 0, s[0:1]
	global_load_dword v13, v[8:9], off
	v_lshl_add_u64 v[8:9], v[8:9], 0, s[0:1]
	global_load_dword v14, v[8:9], off
	v_lshl_add_u64 v[8:9], v[8:9], 0, s[0:1]
	global_load_dword v15, v[8:9], off
	v_lshl_add_u64 v[8:9], v[8:9], 0, s[0:1]
	global_load_dword v16, v[8:9], off
	v_lshl_add_u64 v[8:9], v[8:9], 0, s[0:1]
	global_load_dword v17, v[8:9], off
	s_waitcnt vmcnt(0)
	s_branch .Lpz_store
.Lpz_zero:
	v_mov_b32_e32 v10, 0
	v_mov_b32_e32 v11, 0
	v_mov_b32_e32 v12, 0
	v_mov_b32_e32 v13, 0
	v_mov_b32_e32 v14, 0
	v_mov_b32_e32 v15, 0
	v_mov_b32_e32 v16, 0
	v_mov_b32_e32 v17, 0
.Lpz_store:
	ds_write_b32 v46, v10
	ds_write_b32 v46, v11 offset:2080
	ds_write_b32 v46, v12 offset:4160
	ds_write_b32 v46, v13 offset:6240
	ds_write_b32 v46, v14 offset:8320
	ds_write_b32 v46, v15 offset:10400
	ds_write_b32 v46, v16 offset:12480
	ds_write_b32 v46, v17 offset:14560

.LBB0_1221:
	s_or_b64 exec, exec, s[10:11]
	s_cmpk_lt_i32 s2, 0x800
	s_cselect_b64 s[10:11], -1, 0
	s_and_b64 vcc, exec, s[10:11]
	s_waitcnt lgkmcnt(0)
	s_barrier
	s_cbranch_vccz .LBB0_1224
	v_lshrrev_b32_e32 v0, 6, v141
	v_and_b32_e32 v1, 63, v141
	s_mov_b32 s44, 0xbfb8aa3b
	v_readfirstlane_b32 s13, v0
	s_mov_b32 s45, 0xbfb8aa3b
	v_lshlrev_b32_e32 v4, 4, v1
	v_lshrrev_b32_e32 v2, 3, v1
	v_lshlrev_b32_e32 v0, 5, v1
	v_lshlrev_b32_e32 v5, 2, v2
	v_mul_u32_u24_e32 v6, 0x318000, v2
	global_load_dwordx4 v[8:11], v0, s[46:47]
	global_load_dwordx4 v[12:15], v0, s[46:47] offset:16
	global_load_dwordx4 v[16:19], v0, s[48:49]
	global_load_dwordx4 v[20:23], v0, s[48:49] offset:16
	v_and_b32_e32 v7, 7, v1
	v_lshrrev_b32_e32 v2, 1, v7
	v_and_b32_e32 v7, 1, v7
	v_lshlrev_b32_e32 v2, 9, v2
	v_lshlrev_b32_e32 v7, 6, v7
	v_add3_u32 v7, v6, v2, v7
	v_mov_b32_e32 v100, 0x3a27c5ac
	s_mov_b32 s12, s2
	s_lshl_b32 s16, s12, 3
	s_add_i32 s16, s16, s13
	s_mul_i32 s17, s16, 0x2100
	s_add_u32 s24, s78, s17
	s_addc_u32 s25, s79, 0
	s_add_u32 s26, s24, 0x1900
	s_addc_u32 s27, s25, 0
	s_lshl_b32 s17, s16, 10
	s_add_u32 s28, s80, s17
	s_addc_u32 s29, s81, 0
	s_lshr_b32 s17, s16, 12
	s_lshl_b32 s17, s17, 11
	s_bfe_u32 s19, s16, 0x80004
	s_add_i32 s17, s17, s19
	s_mul_i32 s17, s17, 0x3180
	s_add_u32 s68, s86, s17
	s_addc_u32 s69, s87, 0
	s_and_b32 s19, s16, 15
	s_lshl_b32 s17, s19, 2
	s_addk_i32 s17, 0x3100
	s_add_u32 s30, s68, s17
	s_addc_u32 s31, s69, 0
	s_lshr_b32 s17, s19, 2
	s_lshl_b32 s17, s17, 7
	s_and_b32 s19, s19, 3
	s_lshl_b32 s19, s19, 1
	s_add_i32 s17, s17, s19
	s_addk_i32 s17, 0x2800
	s_add_u32 s70, s68, s17
	s_addc_u32 s71, s69, 0
	global_load_dword v24, v5, s[24:25] offset:3072
	global_load_dword v25, v5, s[24:25] offset:3104
	global_load_dword v26, v5, s[24:25] offset:3136
	global_load_dwordx4 v[28:31], v4, s[24:25] nt
	global_load_dwordx4 v[32:35], v4, s[24:25] offset:1024 nt
	global_load_dwordx4 v[36:39], v4, s[24:25] offset:2048 nt
	global_load_dwordx4 v[44:47], v4, s[26:27] offset:1024 nt
	global_load_dwordx4 v[48:51], v4, s[28:29] nt
	global_load_dwordx4 v[52:55], v4, s[26:27] nt
	global_load_dword v27, v6, s[30:31]
	global_load_ushort v56, v7, s[70:71] offset:0
	global_load_ushort v57, v7, s[70:71] offset:8
	global_load_ushort v58, v7, s[70:71] offset:16
	global_load_ushort v59, v7, s[70:71] offset:24
	global_load_ushort v60, v7, s[70:71] offset:32
	global_load_ushort v61, v7, s[70:71] offset:40
	global_load_ushort v62, v7, s[70:71] offset:48
	global_load_ushort v63, v7, s[70:71] offset:56
	s_mov_b32 s50, 1

.Lmg_wdone:
	v_max3_f32 v127, v24, v25, v26
	v_sub_f32_e32 v102, v24, v127
	v_sub_f32_e32 v104, v25, v127
	v_sub_f32_e32 v106, v26, v127
	v_mul_f32_e32 v102, 0x3fb8aa3b, v102
	v_mul_f32_e32 v104, 0x3fb8aa3b, v104
	v_mul_f32_e32 v106, 0x3fb8aa3b, v106
	v_exp_f32_e32 v102, v102
	v_exp_f32_e32 v104, v104
	v_exp_f32_e32 v106, v106
	s_nop 0
	v_add_f32_e32 v127, v102, v104
	v_add_f32_e32 v127, v106, v127
	v_div_scale_f32 v122, s[36:37], v127, v127, 1.0
	v_rcp_f32_e32 v123, v122
	v_div_scale_f32 v124, vcc, 1.0, v127, 1.0
	v_fma_f32 v126, -v122, v123, 1.0
	v_fmac_f32_e32 v123, v126, v123
	v_mul_f32_e32 v125, v124, v123
	v_fma_f32 v126, -v122, v125, v124
	v_fmac_f32_e32 v125, v126, v123
	v_fma_f32 v122, -v122, v125, v124
	v_div_fmas_f32 v122, v122, v123, v125
	v_div_fixup_f32 v103, v122, v127, 1.0
	v_mul_f32_e32 v102, v102, v103
	v_mul_f32_e32 v104, v104, v103
	v_mul_f32_e32 v106, v106, v103
	v_lshlrev_b32_e32 v108, 16, v28
	v_and_b32_e32 v109, 0xffff0000, v28
	v_lshlrev_b32_e32 v110, 16, v32
	v_and_b32_e32 v111, 0xffff0000, v32
	v_lshlrev_b32_e32 v112, 16, v36
	v_and_b32_e32 v113, 0xffff0000, v36
	v_lshlrev_b32_e32 v114, 16, v44
	v_and_b32_e32 v115, 0xffff0000, v44
	v_pk_mul_f32 v[116:117], v[108:109], v[102:103] op_sel_hi:[1,0]
	v_pk_fma_f32 v[116:117], v[110:111], v[104:105], v[116:117] op_sel_hi:[1,0,1]
	v_pk_fma_f32 v[116:117], v[112:113], v[106:107], v[116:117] op_sel_hi:[1,0,1]
	v_pk_mul_f32 v[118:119], v[114:115], s[44:45]
	v_exp_f32_e32 v118, v118
	v_exp_f32_e32 v119, v119
	s_nop 0
	v_pk_add_f32 v[118:119], v[118:119], 1.0 op_sel_hi:[1,0]
	v_div_scale_f32 v122, s[36:37], v118, v118, v114
	v_rcp_f32_e32 v123, v122
	v_div_scale_f32 v124, vcc, v114, v118, v114
	v_fma_f32 v126, -v122, v123, 1.0
	v_fmac_f32_e32 v123, v126, v123
	v_mul_f32_e32 v125, v124, v123
	v_fma_f32 v126, -v122, v125, v124
	v_fmac_f32_e32 v125, v126, v123
	v_fma_f32 v122, -v122, v125, v124
	v_div_fmas_f32 v122, v122, v123, v125
	v_div_fixup_f32 v120, v122, v118, v114
	v_div_scale_f32 v122, s[36:37], v119, v119, v115
	v_rcp_f32_e32 v123, v122
	v_div_scale_f32 v124, vcc, v115, v119, v115
	v_fma_f32 v126, -v122, v123, 1.0
	v_fmac_f32_e32 v123, v126, v123
	v_mul_f32_e32 v125, v124, v123
	v_fma_f32 v126, -v122, v125, v124
	v_fmac_f32_e32 v125, v126, v123
	v_fma_f32 v122, -v122, v125, v124
	v_div_fmas_f32 v122, v122, v123, v125
	v_div_fixup_f32 v121, v122, v119, v115
	v_pk_mul_f32 v[116:117], v[120:121], v[116:117]
	v_cvt_pk_bf16_f32 v128, v116, v117
	v_lshlrev_b32_e32 v108, 16, v29
	v_and_b32_e32 v109, 0xffff0000, v29
	v_lshlrev_b32_e32 v110, 16, v33
	v_and_b32_e32 v111, 0xffff0000, v33
	v_lshlrev_b32_e32 v112, 16, v37
	v_and_b32_e32 v113, 0xffff0000, v37
	v_lshlrev_b32_e32 v114, 16, v45
	v_and_b32_e32 v115, 0xffff0000, v45
	v_pk_mul_f32 v[116:117], v[108:109], v[102:103] op_sel_hi:[1,0]
	v_pk_fma_f32 v[116:117], v[110:111], v[104:105], v[116:117] op_sel_hi:[1,0,1]
	v_pk_fma_f32 v[116:117], v[112:113], v[106:107], v[116:117] op_sel_hi:[1,0,1]
	v_pk_mul_f32 v[118:119], v[114:115], s[44:45]
	v_exp_f32_e32 v118, v118
	v_exp_f32_e32 v119, v119
	s_nop 0
	v_pk_add_f32 v[118:119], v[118:119], 1.0 op_sel_hi:[1,0]
	v_div_scale_f32 v122, s[36:37], v118, v118, v114
	v_rcp_f32_e32 v123, v122
	v_div_scale_f32 v124, vcc, v114, v118, v114
	v_fma_f32 v126, -v122, v123, 1.0
	v_fmac_f32_e32 v123, v126, v123
	v_mul_f32_e32 v125, v124, v123
	v_fma_f32 v126, -v122, v125, v124
	v_fmac_f32_e32 v125, v126, v123
	v_fma_f32 v122, -v122, v125, v124
	v_div_fmas_f32 v122, v122, v123, v125
	v_div_fixup_f32 v120, v122, v118, v114
	v_div_scale_f32 v122, s[36:37], v119, v119, v115
	v_rcp_f32_e32 v123, v122
	v_div_scale_f32 v124, vcc, v115, v119, v115
	v_fma_f32 v126, -v122, v123, 1.0
	v_fmac_f32_e32 v123, v126, v123
	v_mul_f32_e32 v125, v124, v123
	v_fma_f32 v126, -v122, v125, v124
	v_fmac_f32_e32 v125, v126, v123
	v_fma_f32 v122, -v122, v125, v124
	v_div_fmas_f32 v122, v122, v123, v125
	v_div_fixup_f32 v121, v122, v119, v115
	v_pk_mul_f32 v[116:117], v[120:121], v[116:117]
	v_cvt_pk_bf16_f32 v129, v116, v117
	v_lshlrev_b32_e32 v108, 16, v30
	v_and_b32_e32 v109, 0xffff0000, v30
	v_lshlrev_b32_e32 v110, 16, v34
	v_and_b32_e32 v111, 0xffff0000, v34
	v_lshlrev_b32_e32 v112, 16, v38
	v_and_b32_e32 v113, 0xffff0000, v38
	v_lshlrev_b32_e32 v114, 16, v46
	v_and_b32_e32 v115, 0xffff0000, v46
	v_pk_mul_f32 v[116:117], v[108:109], v[102:103] op_sel_hi:[1,0]
	v_pk_fma_f32 v[116:117], v[110:111], v[104:105], v[116:117] op_sel_hi:[1,0,1]
	v_pk_fma_f32 v[116:117], v[112:113], v[106:107], v[116:117] op_sel_hi:[1,0,1]
	v_pk_mul_f32 v[118:119], v[114:115], s[44:45]
	v_exp_f32_e32 v118, v118
	v_exp_f32_e32 v119, v119
	s_nop 0
	v_pk_add_f32 v[118:119], v[118:119], 1.0 op_sel_hi:[1,0]
	v_div_scale_f32 v122, s[36:37], v118, v118, v114
	v_rcp_f32_e32 v123, v122
	v_div_scale_f32 v124, vcc, v114, v118, v114
	v_fma_f32 v126, -v122, v123, 1.0
	v_fmac_f32_e32 v123, v126, v123
	v_mul_f32_e32 v125, v124, v123
	v_fma_f32 v126, -v122, v125, v124
	v_fmac_f32_e32 v125, v126, v123
	v_fma_f32 v122, -v122, v125, v124
	v_div_fmas_f32 v122, v122, v123, v125
	v_div_fixup_f32 v120, v122, v118, v114
	v_div_scale_f32 v122, s[36:37], v119, v119, v115
	v_rcp_f32_e32 v123, v122
	v_div_scale_f32 v124, vcc, v115, v119, v115
	v_fma_f32 v126, -v122, v123, 1.0
	v_fmac_f32_e32 v123, v126, v123
	v_mul_f32_e32 v125, v124, v123
	v_fma_f32 v126, -v122, v125, v124
	v_fmac_f32_e32 v125, v126, v123
	v_fma_f32 v122, -v122, v125, v124
	v_div_fmas_f32 v122, v122, v123, v125
	v_div_fixup_f32 v121, v122, v119, v115
	v_pk_mul_f32 v[116:117], v[120:121], v[116:117]
	v_cvt_pk_bf16_f32 v130, v116, v117
	v_lshlrev_b32_e32 v108, 16, v31
	v_and_b32_e32 v109, 0xffff0000, v31
	v_lshlrev_b32_e32 v110, 16, v35
	v_and_b32_e32 v111, 0xffff0000, v35
	v_lshlrev_b32_e32 v112, 16, v39
	v_and_b32_e32 v113, 0xffff0000, v39
	v_lshlrev_b32_e32 v114, 16, v47
	v_and_b32_e32 v115, 0xffff0000, v47
	v_pk_mul_f32 v[116:117], v[108:109], v[102:103] op_sel_hi:[1,0]
	v_pk_fma_f32 v[116:117], v[110:111], v[104:105], v[116:117] op_sel_hi:[1,0,1]
	v_pk_fma_f32 v[116:117], v[112:113], v[106:107], v[116:117] op_sel_hi:[1,0,1]
	v_pk_mul_f32 v[118:119], v[114:115], s[44:45]
	v_exp_f32_e32 v118, v118
	v_exp_f32_e32 v119, v119
	s_nop 0
	v_pk_add_f32 v[118:119], v[118:119], 1.0 op_sel_hi:[1,0]
	v_div_scale_f32 v122, s[36:37], v118, v118, v114
	v_rcp_f32_e32 v123, v122
	v_div_scale_f32 v124, vcc, v114, v118, v114
	v_fma_f32 v126, -v122, v123, 1.0
	v_fmac_f32_e32 v123, v126, v123
	v_mul_f32_e32 v125, v124, v123
	v_fma_f32 v126, -v122, v125, v124
	v_fmac_f32_e32 v125, v126, v123
	v_fma_f32 v122, -v122, v125, v124
	v_div_fmas_f32 v122, v122, v123, v125
	v_div_fixup_f32 v120, v122, v118, v114
	v_div_scale_f32 v122, s[36:37], v119, v119, v115
	v_rcp_f32_e32 v123, v122
	v_div_scale_f32 v124, vcc, v115, v119, v115
	v_fma_f32 v126, -v122, v123, 1.0
	v_fmac_f32_e32 v123, v126, v123
	v_mul_f32_e32 v125, v124, v123
	v_fma_f32 v126, -v122, v125, v124
	v_fmac_f32_e32 v125, v126, v123
	v_fma_f32 v122, -v122, v125, v124
	v_div_fmas_f32 v122, v122, v123, v125
	v_div_fixup_f32 v121, v122, v119, v115
	v_pk_mul_f32 v[116:117], v[120:121], v[116:117]
	v_cvt_pk_bf16_f32 v131, v116, v117
	global_store_dwordx4 v4, v[128:131], s[26:27] offset:1024
	v_lshlrev_b32_e32 v28, 16, v48
	v_and_b32_e32 v29, 0xffff0000, v48
	v_lshlrev_b32_e32 v30, 16, v49
	v_and_b32_e32 v31, 0xffff0000, v49
	v_lshlrev_b32_e32 v32, 16, v50
	v_and_b32_e32 v33, 0xffff0000, v50
	v_lshlrev_b32_e32 v34, 16, v51
	v_and_b32_e32 v35, 0xffff0000, v51
	v_lshlrev_b32_e32 v36, 16, v52
	v_and_b32_e32 v37, 0xffff0000, v52
	v_lshlrev_b32_e32 v38, 16, v53
	v_and_b32_e32 v39, 0xffff0000, v53
	v_lshlrev_b32_e32 v44, 16, v54
	v_and_b32_e32 v45, 0xffff0000, v54
	v_lshlrev_b32_e32 v46, 16, v55
	v_and_b32_e32 v47, 0xffff0000, v55
	v_lshlrev_b32_e32 v56, 16, v56
	v_lshlrev_b32_e32 v57, 16, v57
	v_lshlrev_b32_e32 v58, 16, v58
	v_lshlrev_b32_e32 v59, 16, v59
	v_lshlrev_b32_e32 v60, 16, v60
	v_lshlrev_b32_e32 v61, 16, v61
	v_lshlrev_b32_e32 v62, 16, v62
	v_lshlrev_b32_e32 v63, 16, v63
	v_add_f32_e32 v108, v28, v29
	v_add_f32_e32 v108, v108, v30
	v_add_f32_e32 v108, v108, v31
	v_add_f32_e32 v108, v108, v32
	v_add_f32_e32 v108, v108, v33
	v_add_f32_e32 v108, v108, v34
	v_add_f32_e32 v108, v108, v35
	s_nop 1
	v_add_f32_dpp v109, v108, v108 quad_perm:[1,0,3,2] row_mask:0xf bank_mask:0xf
	s_nop 1
	v_add_f32_dpp v108, v109, v109 quad_perm:[2,3,0,1] row_mask:0xf bank_mask:0xf
	s_nop 1
	v_add_f32_dpp v109, v108, v108 row_half_mirror row_mask:0xf bank_mask:0xf
	v_mov_b32_e32 v108, v109
	v_mul_f32_e32 v108, 0x3c800000, v108
	v_pk_add_f32 v[28:29], v[28:29], v[108:109] op_sel_hi:[1,0] neg_lo:[0,1] neg_hi:[0,1]
	v_pk_add_f32 v[30:31], v[30:31], v[108:109] op_sel_hi:[1,0] neg_lo:[0,1] neg_hi:[0,1]
	v_pk_add_f32 v[32:33], v[32:33], v[108:109] op_sel_hi:[1,0] neg_lo:[0,1] neg_hi:[0,1]
	v_pk_add_f32 v[34:35], v[34:35], v[108:109] op_sel_hi:[1,0] neg_lo:[0,1] neg_hi:[0,1]
	v_pk_mul_f32 v[110:111], v[28:29], v[28:29]
	v_pk_mul_f32 v[112:113], v[30:31], v[30:31]
	v_pk_mul_f32 v[114:115], v[32:33], v[32:33]
	v_pk_mul_f32 v[116:117], v[34:35], v[34:35]
	v_add_f32_e32 v118, v110, v111
	v_add_f32_e32 v118, v112, v118
	v_add_f32_e32 v118, v113, v118
	v_add_f32_e32 v118, v114, v118
	v_add_f32_e32 v118, v115, v118
	v_add_f32_e32 v118, v116, v118
	v_add_f32_e32 v118, v117, v118
	s_nop 1
	v_add_f32_dpp v119, v118, v118 quad_perm:[1,0,3,2] row_mask:0xf bank_mask:0xf
	s_nop 1
	v_add_f32_dpp v118, v119, v119 quad_perm:[2,3,0,1] row_mask:0xf bank_mask:0xf
	s_nop 1
	v_add_f32_dpp v119, v118, v118 row_half_mirror row_mask:0xf bank_mask:0xf
	v_mov_b32_e32 v118, v119
	v_fmamk_f32 v118, v118, 0x3c800000, v100
	v_rsq_f32_e32 v118, v118
	v_mov_b32_e32 v120, v27
	v_pk_mul_f32 v[28:29], v[28:29], v[118:119] op_sel_hi:[1,0]
	v_pk_mul_f32 v[30:31], v[30:31], v[118:119] op_sel_hi:[1,0]
	v_pk_mul_f32 v[32:33], v[32:33], v[118:119] op_sel_hi:[1,0]
	v_pk_mul_f32 v[34:35], v[34:35], v[118:119] op_sel_hi:[1,0]
	v_pk_fma_f32 v[28:29], v[8:9], v[28:29], v[16:17]
	v_pk_fma_f32 v[30:31], v[10:11], v[30:31], v[18:19]
	v_pk_fma_f32 v[32:33], v[12:13], v[32:33], v[20:21]
	v_pk_fma_f32 v[34:35], v[14:15], v[34:35], v[22:23]
	v_pk_fma_f32 v[28:29], v[120:121], v[56:57], v[28:29] op_sel_hi:[0,1,1]
	v_pk_fma_f32 v[30:31], v[120:121], v[58:59], v[30:31] op_sel_hi:[0,1,1]
	v_pk_fma_f32 v[32:33], v[120:121], v[60:61], v[32:33] op_sel_hi:[0,1,1]
	v_pk_fma_f32 v[34:35], v[120:121], v[62:63], v[34:35] op_sel_hi:[0,1,1]
	v_pk_mul_f32 v[118:119], v[36:37], s[44:45]
	v_exp_f32_e32 v118, v118
	v_exp_f32_e32 v119, v119
	s_nop 0
	v_pk_add_f32 v[118:119], v[118:119], 1.0 op_sel_hi:[1,0]
	v_div_scale_f32 v122, s[36:37], v118, v118, v36
	v_rcp_f32_e32 v123, v122
	v_div_scale_f32 v124, vcc, v36, v118, v36
	v_fma_f32 v126, -v122, v123, 1.0
	v_fmac_f32_e32 v123, v126, v123
	v_mul_f32_e32 v125, v124, v123
	v_fma_f32 v126, -v122, v125, v124
	v_fmac_f32_e32 v125, v126, v123
	v_fma_f32 v122, -v122, v125, v124
	v_div_fmas_f32 v122, v122, v123, v125
	v_div_fixup_f32 v108, v122, v118, v36
	v_div_scale_f32 v122, s[36:37], v119, v119, v37
	v_rcp_f32_e32 v123, v122
	v_div_scale_f32 v124, vcc, v37, v119, v37
	v_fma_f32 v126, -v122, v123, 1.0
	v_fmac_f32_e32 v123, v126, v123
	v_mul_f32_e32 v125, v124, v123
	v_fma_f32 v126, -v122, v125, v124
	v_fmac_f32_e32 v125, v126, v123
	v_fma_f32 v122, -v122, v125, v124
	v_div_fmas_f32 v122, v122, v123, v125
	v_div_fixup_f32 v109, v122, v119, v37
	v_pk_mul_f32 v[28:29], v[108:109], v[28:29]
	v_cvt_pk_bf16_f32 v132, v28, v29
	v_pk_mul_f32 v[118:119], v[38:39], s[44:45]
	v_exp_f32_e32 v118, v118
	v_exp_f32_e32 v119, v119
	s_nop 0
	v_pk_add_f32 v[118:119], v[118:119], 1.0 op_sel_hi:[1,0]
	v_div_scale_f32 v122, s[36:37], v118, v118, v38
	v_rcp_f32_e32 v123, v122
	v_div_scale_f32 v124, vcc, v38, v118, v38
	v_fma_f32 v126, -v122, v123, 1.0
	v_fmac_f32_e32 v123, v126, v123
	v_mul_f32_e32 v125, v124, v123
	v_fma_f32 v126, -v122, v125, v124
	v_fmac_f32_e32 v125, v126, v123
	v_fma_f32 v122, -v122, v125, v124
	v_div_fmas_f32 v122, v122, v123, v125
	v_div_fixup_f32 v108, v122, v118, v38
	v_div_scale_f32 v122, s[36:37], v119, v119, v39
	v_rcp_f32_e32 v123, v122
	v_div_scale_f32 v124, vcc, v39, v119, v39
	v_fma_f32 v126, -v122, v123, 1.0
	v_fmac_f32_e32 v123, v126, v123
	v_mul_f32_e32 v125, v124, v123
	v_fma_f32 v126, -v122, v125, v124
	v_fmac_f32_e32 v125, v126, v123
	v_fma_f32 v122, -v122, v125, v124
	v_div_fmas_f32 v122, v122, v123, v125
	v_div_fixup_f32 v109, v122, v119, v39
	v_pk_mul_f32 v[30:31], v[108:109], v[30:31]
	v_cvt_pk_bf16_f32 v133, v30, v31
	v_pk_mul_f32 v[118:119], v[44:45], s[44:45]
	v_exp_f32_e32 v118, v118
	v_exp_f32_e32 v119, v119
	s_nop 0
	v_pk_add_f32 v[118:119], v[118:119], 1.0 op_sel_hi:[1,0]
	v_div_scale_f32 v122, s[36:37], v118, v118, v44
	v_rcp_f32_e32 v123, v122
	v_div_scale_f32 v124, vcc, v44, v118, v44
	v_fma_f32 v126, -v122, v123, 1.0
	v_fmac_f32_e32 v123, v126, v123
	v_mul_f32_e32 v125, v124, v123
	v_fma_f32 v126, -v122, v125, v124
	v_fmac_f32_e32 v125, v126, v123
	v_fma_f32 v122, -v122, v125, v124
	v_div_fmas_f32 v122, v122, v123, v125
	v_div_fixup_f32 v108, v122, v118, v44
	v_div_scale_f32 v122, s[36:37], v119, v119, v45
	v_rcp_f32_e32 v123, v122
	v_div_scale_f32 v124, vcc, v45, v119, v45
	v_fma_f32 v126, -v122, v123, 1.0
	v_fmac_f32_e32 v123, v126, v123
	v_mul_f32_e32 v125, v124, v123
	v_fma_f32 v126, -v122, v125, v124
	v_fmac_f32_e32 v125, v126, v123
	v_fma_f32 v122, -v122, v125, v124
	v_div_fmas_f32 v122, v122, v123, v125
	v_div_fixup_f32 v109, v122, v119, v45
	v_pk_mul_f32 v[32:33], v[108:109], v[32:33]
	v_cvt_pk_bf16_f32 v134, v32, v33
	v_pk_mul_f32 v[118:119], v[46:47], s[44:45]
	v_exp_f32_e32 v118, v118
	v_exp_f32_e32 v119, v119
	s_nop 0
	v_pk_add_f32 v[118:119], v[118:119], 1.0 op_sel_hi:[1,0]
	v_div_scale_f32 v122, s[36:37], v118, v118, v46
	v_rcp_f32_e32 v123, v122
	v_div_scale_f32 v124, vcc, v46, v118, v46
	v_fma_f32 v126, -v122, v123, 1.0
	v_fmac_f32_e32 v123, v126, v123
	v_mul_f32_e32 v125, v124, v123
	v_fma_f32 v126, -v122, v125, v124
	v_fmac_f32_e32 v125, v126, v123
	v_fma_f32 v122, -v122, v125, v124
	v_div_fmas_f32 v122, v122, v123, v125
	v_div_fixup_f32 v108, v122, v118, v46
	v_div_scale_f32 v122, s[36:37], v119, v119, v47
	v_rcp_f32_e32 v123, v122
	v_div_scale_f32 v124, vcc, v47, v119, v47
	v_fma_f32 v126, -v122, v123, 1.0
	v_fmac_f32_e32 v123, v126, v123
	v_mul_f32_e32 v125, v124, v123
	v_fma_f32 v126, -v122, v125, v124
	v_fmac_f32_e32 v125, v126, v123
	v_fma_f32 v122, -v122, v125, v124
	v_div_fmas_f32 v122, v122, v123, v125
	v_div_fixup_f32 v109, v122, v119, v47
	v_pk_mul_f32 v[34:35], v[108:109], v[34:35]
	v_cvt_pk_bf16_f32 v135, v34, v35
	global_store_dwordx4 v4, v[132:135], s[26:27]
	s_mov_b32 s50, 0
	s_add_i32 s12, s12, s90
	s_cmpk_lt_i32 s12, 0x800
	s_cbranch_scc0 .Lmg_nonext
	s_lshl_b32 s16, s12, 3
	s_add_i32 s16, s16, s13
	s_mul_i32 s17, s16, 0x2100
	s_add_u32 s24, s78, s17
	s_addc_u32 s25, s79, 0
	s_add_u32 s26, s24, 0x1900
	s_addc_u32 s27, s25, 0
	s_lshl_b32 s17, s16, 10
	s_add_u32 s28, s80, s17
	s_addc_u32 s29, s81, 0
	s_lshr_b32 s17, s16, 12
	s_lshl_b32 s17, s17, 11
	s_bfe_u32 s19, s16, 0x80004
	s_add_i32 s17, s17, s19
	s_mul_i32 s17, s17, 0x3180
	s_add_u32 s68, s86, s17
	s_addc_u32 s69, s87, 0
	s_and_b32 s19, s16, 15
	s_lshl_b32 s17, s19, 2
	s_addk_i32 s17, 0x3100
	s_add_u32 s30, s68, s17
	s_addc_u32 s31, s69, 0
	s_lshr_b32 s17, s19, 2
	s_lshl_b32 s17, s17, 7
	s_and_b32 s19, s19, 3
	s_lshl_b32 s19, s19, 1
	s_add_i32 s17, s17, s19
	s_addk_i32 s17, 0x2800
	s_add_u32 s70, s68, s17
	s_addc_u32 s71, s69, 0
	global_load_dword v24, v5, s[24:25] offset:3072
	global_load_dword v25, v5, s[24:25] offset:3104
	global_load_dword v26, v5, s[24:25] offset:3136
	global_load_dwordx4 v[28:31], v4, s[24:25] nt
	global_load_dwordx4 v[32:35], v4, s[24:25] offset:1024 nt
	global_load_dwordx4 v[36:39], v4, s[24:25] offset:2048 nt
	global_load_dwordx4 v[44:47], v4, s[26:27] offset:1024 nt
	global_load_dwordx4 v[48:51], v4, s[28:29] nt
	global_load_dwordx4 v[52:55], v4, s[26:27] nt
	global_load_dword v27, v6, s[30:31]
	global_load_ushort v56, v7, s[70:71] offset:0
	global_load_ushort v57, v7, s[70:71] offset:8
	global_load_ushort v58, v7, s[70:71] offset:16
	global_load_ushort v59, v7, s[70:71] offset:24
	global_load_ushort v60, v7, s[70:71] offset:32
	global_load_ushort v61, v7, s[70:71] offset:40
	global_load_ushort v62, v7, s[70:71] offset:48
	global_load_ushort v63, v7, s[70:71] offset:56
	s_waitcnt vmcnt(20)
	s_branch .Lmg_cb
